# attention: per-row sum of squares of the normalised O accumulated by two packed-FMA chains (18 VALU) instead of 16 packed squares + 31 serial adds
# baseline (speedup 1.0000x reference)
.LBB0_320:
	v_cndmask_b32_e64 v74, v188, v49, s[10:11]
	v_max3_f32 v49, v120, s97, v189
	v_max3_f32 v49, v49, v161, v159
	v_max3_f32 v49, v49, v157, v126
	v_max3_f32 v49, v49, v123, v122
	v_max3_f32 v49, v49, v121, v73
	v_max3_f32 v49, v49, v72, v71
	v_max3_f32 v49, v49, v70, v69
	v_max3_f32 v49, v49, v68, v67
	v_max3_f32 v49, v49, v32, v33
	v_max3_f32 v49, v49, v34, v35
	v_max3_f32 v49, v49, v36, v37
	v_max3_f32 v49, v49, v38, v39
	v_max3_f32 v49, v49, v40, v41
	v_max3_f32 v49, v49, v42, v43
	v_max3_f32 v49, v49, v44, v45
	v_max3_f32 v49, v49, v46, v47
	v_max3_f32 v49, v49, v16, v17
	v_max3_f32 v49, v49, v18, v19
	v_max3_f32 v49, v49, v20, v21
	v_max3_f32 v49, v49, v22, v23
	v_max3_f32 v49, v49, v24, v25
	v_max3_f32 v49, v49, v26, v27
	v_max3_f32 v49, v49, v28, v29
	v_max3_f32 v49, v49, v30, v31
	v_max3_f32 v49, v49, v0, v1
	v_max3_f32 v49, v49, v2, v3
	v_max3_f32 v49, v49, v4, v5
	v_max3_f32 v49, v49, v6, v7
	v_max3_f32 v49, v49, v8, v9
	v_max3_f32 v49, v49, v10, v11
	v_cndmask_b32_e64 v64, v48, v188, s[8:9]
	v_max3_f32 v49, v49, v12, v13
	v_cndmask_b32_e64 v75, v64, v48, s[10:11]
	v_max3_f32 v49, v49, v14, v15
	v_cndmask_b32_e64 v76, v50, v188, s[12:13]
	v_cndmask_b32_e64 v77, v51, v188, s[14:15]
	v_max3_f32 v49, v49, v75, v74
	v_cndmask_b32_e64 v78, v52, v188, s[16:17]
	v_cndmask_b32_e64 v66, v53, v188, s[18:19]
	v_max3_f32 v49, v49, v76, v77
	v_cndmask_b32_e64 v65, v54, v188, s[20:21]
	v_cndmask_b32_e64 v64, v55, v188, s[22:23]
	v_max3_f32 v49, v49, v78, v66
	v_cndmask_b32_e64 v56, v56, v188, s[24:25]
	v_cndmask_b32_e64 v55, v57, v188, s[26:27]
	v_max3_f32 v49, v49, v65, v64
	v_cndmask_b32_e64 v54, v58, v188, s[28:29]
	v_cndmask_b32_e64 v53, v59, v188, s[30:31]
	v_max3_f32 v49, v49, v56, v55
	v_cndmask_b32_e64 v52, v60, v188, s[34:35]
	v_cndmask_b32_e64 v51, v61, v188, s[36:37]
	v_max3_f32 v49, v49, v54, v53
	v_cndmask_b32_e64 v50, v62, v188, s[38:39]
	v_cndmask_b32_e64 v48, v63, v188, s[40:41]
	v_max3_f32 v49, v49, v52, v51
	v_max3_f32 v49, v49, v50, v48
	ds_bpermute_b32 v57, v171, v49
	v_add_u32_e32 v228, s69, v175
	s_waitcnt lgkmcnt(0)
	v_max_f32_e32 v57, v57, v57
	v_max_f32_e32 v49, v49, v57
	v_sub_f32_e32 v57, v120, v49
	v_exp_f32_e32 v57, v57
	v_sub_f32_e32 v58, v189, v49
	v_exp_f32_e32 v58, v58
	v_sub_f32_e32 v59, v161, v49
	v_exp_f32_e32 v59, v59
	v_sub_f32_e32 v61, v159, v49
	v_exp_f32_e32 v61, v61
	v_sub_f32_e32 v62, v157, v49
	v_add_f32_e32 v60, 0, v57
	v_exp_f32_e32 v62, v62
	v_sub_f32_e32 v63, v126, v49
	v_add_f32_e32 v60, v58, v60
	v_exp_f32_e32 v63, v63
	v_sub_f32_e32 v79, v123, v49
	v_add_f32_e32 v60, v59, v60
	v_exp_f32_e32 v79, v79
	v_sub_f32_e32 v120, v122, v49
	v_add_f32_e32 v60, v61, v60
	v_exp_f32_e32 v120, v120
	v_sub_f32_e32 v121, v121, v49
	v_add_f32_e32 v60, v62, v60
	v_exp_f32_e32 v121, v121
	v_sub_f32_e32 v73, v73, v49
	v_add_f32_e32 v60, v63, v60
	v_exp_f32_e32 v73, v73
	v_sub_f32_e32 v72, v72, v49
	v_add_f32_e32 v60, v79, v60
	v_exp_f32_e32 v72, v72
	v_sub_f32_e32 v71, v71, v49
	v_add_f32_e32 v60, v120, v60
	v_exp_f32_e32 v71, v71
	v_sub_f32_e32 v70, v70, v49
	v_add_f32_e32 v60, v121, v60
	v_exp_f32_e32 v70, v70
	v_sub_f32_e32 v69, v69, v49
	v_add_f32_e32 v60, v73, v60
	v_exp_f32_e32 v69, v69
	v_sub_f32_e32 v68, v68, v49
	v_add_f32_e32 v60, v72, v60
	v_exp_f32_e32 v68, v68
	v_sub_f32_e32 v67, v67, v49
	v_add_f32_e32 v60, v71, v60
	v_exp_f32_e32 v67, v67
	v_sub_f32_e32 v32, v32, v49
	v_add_f32_e32 v60, v70, v60
	v_exp_f32_e32 v122, v32
	v_sub_f32_e32 v32, v33, v49
	v_add_f32_e32 v60, v69, v60
	v_exp_f32_e32 v123, v32
	v_sub_f32_e32 v32, v34, v49
	v_add_f32_e32 v60, v68, v60
	v_exp_f32_e32 v126, v32
	v_sub_f32_e32 v33, v35, v49
	v_add_f32_e32 v32, v67, v60
	v_exp_f32_e32 v60, v33
	v_sub_f32_e32 v33, v36, v49
	v_add_f32_e32 v32, v122, v32
	v_exp_f32_e32 v157, v33
	v_sub_f32_e32 v33, v37, v49
	v_add_f32_e32 v32, v123, v32
	v_exp_f32_e32 v159, v33
	v_sub_f32_e32 v33, v38, v49
	v_add_f32_e32 v32, v126, v32
	v_exp_f32_e32 v161, v33
	v_sub_f32_e32 v33, v39, v49
	v_add_f32_e32 v32, v60, v32
	v_exp_f32_e32 v189, v33
	v_sub_f32_e32 v33, v40, v49
	v_add_f32_e32 v32, v157, v32
	v_exp_f32_e32 v190, v33
	v_sub_f32_e32 v33, v41, v49
	v_add_f32_e32 v32, v159, v32
	v_exp_f32_e32 v191, v33
	v_sub_f32_e32 v33, v42, v49
	v_add_f32_e32 v32, v161, v32
	v_exp_f32_e32 v192, v33
	v_sub_f32_e32 v33, v43, v49
	v_add_f32_e32 v32, v189, v32
	v_exp_f32_e32 v198, v33
	v_sub_f32_e32 v33, v44, v49
	v_add_f32_e32 v32, v190, v32
	v_exp_f32_e32 v199, v33
	v_sub_f32_e32 v33, v45, v49
	v_add_f32_e32 v32, v191, v32
	v_exp_f32_e32 v200, v33
	v_sub_f32_e32 v33, v46, v49
	v_add_f32_e32 v32, v192, v32
	v_exp_f32_e32 v201, v33
	v_sub_f32_e32 v33, v47, v49
	v_add_f32_e32 v32, v198, v32
	v_exp_f32_e32 v202, v33
	v_sub_f32_e32 v16, v16, v49
	v_add_f32_e32 v32, v199, v32
	v_exp_f32_e32 v203, v16
	v_sub_f32_e32 v16, v17, v49
	v_add_f32_e32 v32, v200, v32
	v_exp_f32_e32 v204, v16
	v_sub_f32_e32 v16, v18, v49
	v_add_f32_e32 v32, v201, v32
	v_exp_f32_e32 v205, v16
	v_sub_f32_e32 v17, v19, v49
	v_add_f32_e32 v16, v202, v32
	v_exp_f32_e32 v206, v17
	v_sub_f32_e32 v17, v20, v49
	v_add_f32_e32 v16, v203, v16
	v_exp_f32_e32 v207, v17
	v_sub_f32_e32 v17, v21, v49
	v_add_f32_e32 v16, v204, v16
	v_exp_f32_e32 v208, v17
	v_sub_f32_e32 v17, v22, v49
	v_add_f32_e32 v16, v205, v16
	v_exp_f32_e32 v209, v17
	v_sub_f32_e32 v17, v23, v49
	v_add_f32_e32 v16, v206, v16
	v_exp_f32_e32 v210, v17
	v_sub_f32_e32 v17, v24, v49
	v_add_f32_e32 v16, v207, v16
	v_exp_f32_e32 v211, v17
	v_sub_f32_e32 v17, v25, v49
	v_add_f32_e32 v16, v208, v16
	v_exp_f32_e32 v212, v17
	v_sub_f32_e32 v17, v26, v49
	v_add_f32_e32 v16, v209, v16
	v_exp_f32_e32 v213, v17
	v_sub_f32_e32 v17, v27, v49
	v_add_f32_e32 v16, v210, v16
	v_exp_f32_e32 v214, v17
	v_sub_f32_e32 v17, v28, v49
	v_add_f32_e32 v16, v211, v16
	v_exp_f32_e32 v215, v17
	v_sub_f32_e32 v17, v29, v49
	v_add_f32_e32 v16, v212, v16
	v_exp_f32_e32 v216, v17
	v_sub_f32_e32 v17, v30, v49
	v_add_f32_e32 v16, v213, v16
	v_exp_f32_e32 v217, v17
	v_sub_f32_e32 v17, v31, v49
	v_add_f32_e32 v16, v214, v16
	v_exp_f32_e32 v218, v17
	v_sub_f32_e32 v0, v0, v49
	v_add_f32_e32 v16, v215, v16
	v_exp_f32_e32 v219, v0
	v_sub_f32_e32 v0, v1, v49
	v_add_f32_e32 v16, v216, v16
	v_exp_f32_e32 v220, v0
	v_sub_f32_e32 v0, v2, v49
	v_add_f32_e32 v16, v217, v16
	v_exp_f32_e32 v221, v0
	v_sub_f32_e32 v1, v3, v49
	v_add_f32_e32 v0, v218, v16
	v_exp_f32_e32 v222, v1
	v_sub_f32_e32 v1, v4, v49
	v_add_f32_e32 v0, v219, v0
	v_exp_f32_e32 v223, v1
	v_sub_f32_e32 v1, v5, v49
	v_add_f32_e32 v0, v220, v0
	v_exp_f32_e32 v224, v1
	v_sub_f32_e32 v1, v6, v49
	v_add_f32_e32 v0, v221, v0
	v_exp_f32_e32 v225, v1
	v_add_f32_e32 v0, v222, v0
	v_add_f32_e32 v0, v223, v0
	v_add_f32_e32 v0, v224, v0
	v_add_f32_e32 v4, v225, v0
	v_sub_f32_e32 v0, v7, v49
	v_exp_f32_e32 v226, v0
	v_sub_f32_e32 v0, v8, v49
	v_exp_f32_e32 v227, v0
	ds_read2_b64 v[0:3], v228 offset1:2
	v_add_f32_e32 v4, v226, v4
	v_cvt_pk_bf16_f32 v5, v59, v61
	v_add_f32_e32 v229, v227, v4
	v_cvt_pk_bf16_f32 v4, v57, v58
	v_cvt_pk_bf16_f32 v6, v62, v63
	v_cvt_pk_bf16_f32 v7, v79, v120
	v_add_u32_e32 v57, s69, v174
	ds_read2_b64 v[16:19], v57 offset1:2
	s_waitcnt lgkmcnt(1)
	v_mfma_f32_32x32x16_bf16 v[32:47], v[0:3], v[4:7], 0
	v_sub_f32_e32 v0, v9, v49
	v_exp_f32_e32 v58, v0
	v_sub_f32_e32 v0, v10, v49
	v_exp_f32_e32 v59, v0
	v_sub_f32_e32 v0, v11, v49
	v_exp_f32_e32 v61, v0
	ds_read2_b64 v[0:3], v228 offset0:4 offset1:6
	s_waitcnt lgkmcnt(1)
	v_mfma_f32_32x32x16_bf16 v[16:31], v[16:19], v[4:7], 0
	v_sub_f32_e32 v4, v12, v49
	v_exp_f32_e32 v12, v4
	v_cvt_pk_bf16_f32 v8, v121, v73
	v_cvt_pk_bf16_f32 v9, v72, v71
	v_cvt_pk_bf16_f32 v10, v70, v69
	v_cvt_pk_bf16_f32 v11, v68, v67
	ds_read2_b64 v[4:7], v57 offset0:4 offset1:6
	v_sub_f32_e32 v48, v48, v49
	s_waitcnt lgkmcnt(1)
	v_mfma_f32_32x32x16_bf16 v[32:47], v[0:3], v[8:11], v[32:47]
	v_add_f32_e32 v0, v58, v229
	v_add_f32_e32 v0, v59, v0
	v_add_f32_e32 v0, v61, v0
	v_add_f32_e32 v62, v12, v0
	v_sub_f32_e32 v0, v13, v49
	v_exp_f32_e32 v13, v0
	ds_read2_b64 v[0:3], v228 offset0:8 offset1:10
	s_waitcnt lgkmcnt(1)
	v_mfma_f32_32x32x16_bf16 v[16:31], v[4:7], v[8:11], v[16:31]
	v_sub_f32_e32 v4, v14, v49
	v_exp_f32_e32 v14, v4
	v_cvt_pk_bf16_f32 v4, v122, v123
	v_cvt_pk_bf16_f32 v5, v126, v60
	v_cvt_pk_bf16_f32 v6, v157, v159
	v_cvt_pk_bf16_f32 v7, v161, v189
	ds_read2_b64 v[8:11], v57 offset0:8 offset1:10
	v_exp_f32_e32 v48, v48
	s_waitcnt lgkmcnt(1)
	v_mfma_f32_32x32x16_bf16 v[32:47], v[0:3], v[4:7], v[32:47]
	v_add_f32_e32 v0, v13, v62
	v_add_f32_e32 v60, v14, v0
	v_sub_f32_e32 v0, v15, v49
	v_exp_f32_e32 v15, v0
	v_sub_f32_e32 v0, v75, v49
	v_exp_f32_e32 v62, v0
	ds_read2_b64 v[0:3], v228 offset0:12 offset1:14
	s_waitcnt lgkmcnt(1)
	v_mfma_f32_32x32x16_bf16 v[16:31], v[8:11], v[4:7], v[16:31]
	v_add_f32_e32 v4, v15, v60
	v_add_f32_e32 v60, v62, v4
	v_cvt_pk_bf16_f32 v4, v190, v191
	v_cvt_pk_bf16_f32 v5, v192, v198
	v_cvt_pk_bf16_f32 v6, v199, v200
	v_cvt_pk_bf16_f32 v7, v201, v202
	ds_read2_b64 v[8:11], v57 offset0:12 offset1:14
	s_waitcnt lgkmcnt(1)
	v_mfma_f32_32x32x16_bf16 v[32:47], v[0:3], v[4:7], v[32:47]
	v_sub_f32_e32 v0, v74, v49
	v_exp_f32_e32 v63, v0
	v_sub_f32_e32 v0, v76, v49
	v_exp_f32_e32 v67, v0
	v_sub_f32_e32 v0, v77, v49
	v_exp_f32_e32 v68, v0
	ds_read2_b64 v[0:3], v228 offset0:16 offset1:18
	s_waitcnt lgkmcnt(1)
	v_mfma_f32_32x32x16_bf16 v[16:31], v[8:11], v[4:7], v[16:31]
	v_sub_f32_e32 v4, v78, v49
	v_exp_f32_e32 v69, v4
	v_cvt_pk_bf16_f32 v4, v203, v204
	v_cvt_pk_bf16_f32 v5, v205, v206
	v_cvt_pk_bf16_f32 v6, v207, v208
	v_cvt_pk_bf16_f32 v7, v209, v210
	ds_read2_b64 v[8:11], v57 offset0:16 offset1:18
	s_waitcnt lgkmcnt(1)
	v_mfma_f32_32x32x16_bf16 v[32:47], v[0:3], v[4:7], v[32:47]
	v_add_f32_e32 v0, v63, v60
	v_add_f32_e32 v0, v67, v0
	v_add_f32_e32 v0, v68, v0
	v_add_f32_e32 v60, v69, v0
	v_sub_f32_e32 v0, v66, v49
	v_exp_f32_e32 v66, v0
	ds_read2_b64 v[0:3], v228 offset0:20 offset1:22
	s_waitcnt lgkmcnt(1)
	v_mfma_f32_32x32x16_bf16 v[16:31], v[8:11], v[4:7], v[16:31]
	v_sub_f32_e32 v4, v65, v49
	v_exp_f32_e32 v65, v4
	v_cvt_pk_bf16_f32 v4, v211, v212
	v_cvt_pk_bf16_f32 v5, v213, v214
	v_cvt_pk_bf16_f32 v6, v215, v216
	v_cvt_pk_bf16_f32 v7, v217, v218
	ds_read2_b64 v[8:11], v57 offset0:20 offset1:22
	s_waitcnt lgkmcnt(1)
	v_mfma_f32_32x32x16_bf16 v[32:47], v[0:3], v[4:7], v[32:47]
	v_add_f32_e32 v0, v66, v60
	v_add_f32_e32 v60, v65, v0
	v_sub_f32_e32 v0, v64, v49
	v_exp_f32_e32 v64, v0
	v_sub_f32_e32 v0, v56, v49
	v_exp_f32_e32 v56, v0
	ds_read2_b64 v[0:3], v228 offset0:24 offset1:26
	s_waitcnt lgkmcnt(1)
	v_mfma_f32_32x32x16_bf16 v[16:31], v[8:11], v[4:7], v[16:31]
	v_sub_f32_e32 v4, v55, v49
	v_exp_f32_e32 v55, v4
	v_cvt_pk_bf16_f32 v4, v219, v220
	v_cvt_pk_bf16_f32 v5, v221, v222
	v_cvt_pk_bf16_f32 v6, v223, v224
	v_cvt_pk_bf16_f32 v7, v225, v226
	ds_read2_b64 v[8:11], v57 offset0:24 offset1:26
	s_waitcnt lgkmcnt(1)
	v_mfma_f32_32x32x16_bf16 v[32:47], v[0:3], v[4:7], v[32:47]
	v_sub_f32_e32 v0, v54, v49
	v_exp_f32_e32 v54, v0
	v_add_f32_e32 v0, v64, v60
	v_add_f32_e32 v0, v56, v0
	v_add_f32_e32 v0, v55, v0
	v_add_f32_e32 v60, v54, v0
	ds_read2_b64 v[0:3], v228 offset0:28 offset1:30
	s_waitcnt lgkmcnt(1)
	v_mfma_f32_32x32x16_bf16 v[16:31], v[8:11], v[4:7], v[16:31]
	v_sub_f32_e32 v4, v53, v49
	v_exp_f32_e32 v53, v4
	v_cvt_pk_bf16_f32 v4, v227, v58
	v_cvt_pk_bf16_f32 v5, v59, v61
	v_cvt_pk_bf16_f32 v6, v12, v13
	v_cvt_pk_bf16_f32 v7, v14, v15
	ds_read2_b64 v[8:11], v57 offset0:28 offset1:30
	v_sub_f32_e32 v15, v50, v49
	s_waitcnt lgkmcnt(1)
	v_mfma_f32_32x32x16_bf16 v[32:47], v[0:3], v[4:7], v[32:47]
	v_sub_f32_e32 v0, v52, v49
	v_exp_f32_e32 v13, v0
	v_sub_f32_e32 v0, v51, v49
	v_exp_f32_e32 v14, v0
	ds_read2_b64 v[0:3], v228 offset0:32 offset1:34
	v_exp_f32_e32 v15, v15
	v_add_f32_e32 v12, v53, v60
	s_waitcnt lgkmcnt(1)
	v_mfma_f32_32x32x16_bf16 v[16:31], v[8:11], v[4:7], v[16:31]
	v_cvt_pk_bf16_f32 v4, v62, v63
	v_cvt_pk_bf16_f32 v5, v67, v68
	v_cvt_pk_bf16_f32 v6, v69, v66
	v_cvt_pk_bf16_f32 v7, v65, v64
	ds_read2_b64 v[8:11], v57 offset0:32 offset1:34
	s_waitcnt lgkmcnt(1)
	v_mfma_f32_32x32x16_bf16 v[32:47], v[0:3], v[4:7], v[32:47]
	v_add_f32_e32 v0, v13, v12
	v_add_f32_e32 v0, v14, v0
	v_add_f32_e32 v0, v15, v0
	v_add_f32_e32 v12, v48, v0
	ds_read2_b64 v[0:3], v228 offset0:36 offset1:38
	ds_bpermute_b32 v50, v171, v12
	s_waitcnt lgkmcnt(2)
	v_mfma_f32_32x32x16_bf16 v[16:31], v[8:11], v[4:7], v[16:31]
	v_sub_f32_e32 v4, v155, v49
	v_exp_f32_e32 v49, v4
	v_cvt_pk_bf16_f32 v4, v56, v55
	v_cvt_pk_bf16_f32 v5, v54, v53
	v_cvt_pk_bf16_f32 v6, v13, v14
	v_cvt_pk_bf16_f32 v7, v15, v48
	ds_read2_b64 v[8:11], v57 offset0:36 offset1:38
	s_waitcnt lgkmcnt(2)
	v_mfma_f32_32x32x16_bf16 v[32:47], v[0:3], v[4:7], v[32:47]
	s_waitcnt lgkmcnt(1)
	v_add_f32_e32 v0, v12, v50
	v_add_f32_e32 v0, v49, v0
	v_div_scale_f32 v1, s[74:75], v0, v0, 1.0
	v_rcp_f32_e32 v2, v1
	s_nop 0
	v_fma_f32 v3, -v1, v2, 1.0
	v_fmac_f32_e32 v2, v3, v2
	v_div_scale_f32 v3, vcc, 1.0, v0, 1.0
	s_waitcnt lgkmcnt(0)
	v_mfma_f32_32x32x16_bf16 v[16:31], v[8:11], v[4:7], v[16:31]
	v_mul_f32_e32 v4, v3, v2
	v_fma_f32 v5, -v1, v4, v3
	v_fmac_f32_e32 v4, v5, v2
	v_fma_f32 v1, -v1, v4, v3
	v_div_fmas_f32 v1, v1, v2, v4
	v_div_fixup_f32 v48, v1, v0, 1.0
	v_pk_mul_f32 v[0:1], v[32:33], v[48:49] op_sel_hi:[1,0]
	v_pk_mul_f32 v[2:3], v[34:35], v[48:49] op_sel_hi:[1,0]
	v_pk_mul_f32 v[50:51], v[0:1], v[0:1]
	v_pk_mul_f32 v[34:35], v[2:3], v[2:3]
	v_pk_mul_f32 v[4:5], v[36:37], v[48:49] op_sel_hi:[1,0]
	v_pk_mul_f32 v[6:7], v[38:39], v[48:49] op_sel_hi:[1,0]
	v_pk_mul_f32 v[8:9], v[40:41], v[48:49] op_sel_hi:[1,0]
	v_pk_mul_f32 v[10:11], v[42:43], v[48:49] op_sel_hi:[1,0]
	v_pk_mul_f32 v[12:13], v[44:45], v[48:49] op_sel_hi:[1,0]
	v_pk_mul_f32 v[32:33], v[46:47], v[48:49] op_sel_hi:[1,0]
	v_pk_mul_f32 v[14:15], v[16:17], v[48:49] op_sel_hi:[1,0]
	v_pk_mul_f32 v[16:17], v[18:19], v[48:49] op_sel_hi:[1,0]
	v_pk_mul_f32 v[18:19], v[20:21], v[48:49] op_sel_hi:[1,0]
	v_pk_mul_f32 v[20:21], v[22:23], v[48:49] op_sel_hi:[1,0]
	v_pk_mul_f32 v[22:23], v[24:25], v[48:49] op_sel_hi:[1,0]
	v_pk_mul_f32 v[24:25], v[26:27], v[48:49] op_sel_hi:[1,0]
	v_pk_mul_f32 v[26:27], v[28:29], v[48:49] op_sel_hi:[1,0]
	v_pk_mul_f32 v[28:29], v[30:31], v[48:49] op_sel_hi:[1,0]
	v_pk_fma_f32 v[50:51], v[4:5], v[4:5], v[50:51]
	v_pk_fma_f32 v[34:35], v[6:7], v[6:7], v[34:35]
	v_pk_fma_f32 v[50:51], v[8:9], v[8:9], v[50:51]
	v_pk_fma_f32 v[34:35], v[10:11], v[10:11], v[34:35]
	v_pk_fma_f32 v[50:51], v[12:13], v[12:13], v[50:51]
	v_pk_fma_f32 v[34:35], v[32:33], v[32:33], v[34:35]
	v_pk_fma_f32 v[50:51], v[14:15], v[14:15], v[50:51]
	v_pk_fma_f32 v[34:35], v[16:17], v[16:17], v[34:35]
	v_pk_fma_f32 v[50:51], v[18:19], v[18:19], v[50:51]
	v_pk_fma_f32 v[34:35], v[20:21], v[20:21], v[34:35]
	v_pk_fma_f32 v[50:51], v[22:23], v[22:23], v[50:51]
	v_pk_fma_f32 v[34:35], v[24:25], v[24:25], v[34:35]
	v_pk_fma_f32 v[50:51], v[26:27], v[26:27], v[50:51]
	v_pk_fma_f32 v[34:35], v[28:29], v[28:29], v[34:35]
	v_pk_add_f32 v[50:51], v[50:51], v[34:35]
	v_add_f32_e32 v30, v50, v51
	ds_bpermute_b32 v31, v171, v30
	s_and_saveexec_b64 s[74:75], s[6:7]
	s_cbranch_execz .LBB0_314
	s_waitcnt lgkmcnt(0)
	v_add_f32_e32 v30, v30, v31
	ds_write_b32 v151, v30
	s_branch .LBB0_314

.LBB0_522:
	s_nop 0
	s_cmp_lt_i32 s80, 7
	s_cselect_b64 s[0:1], -1, 0
	s_cmp_gt_i32 s81, 6
	s_cselect_b64 s[4:5], -1, 0
	s_and_b64 s[0:1], s[0:1], s[4:5]
	s_andn2_b64 vcc, exec, s[0:1]
	s_cbranch_vccnz .LBB0_622
	v_lshrrev_b32_e32 v2, 1, v144
	v_lshrrev_b32_e32 v3, 5, v144
	v_and_b32_e32 v2, 24, v2
	v_and_b32_e32 v3, 4, v3
	v_bfe_u32 v4, v144, 2, 2
	v_lshlrev_b32_e32 v0, 4, v144
	v_and_b32_e32 v1, 32, v144
	v_bfe_u32 v10, v144, 2, 4
	v_or3_b32 v2, v3, v4, v2
	v_lshrrev_b32_e32 v3, 3, v144
	s_movk_i32 s0, 0x70
	v_bitop3_b32 v8, v0, v1, 48 bitop3:0x6c
	v_and_b32_e32 v9, 64, v144
	v_and_or_b32 v4, v3, s0, v10
	s_movk_i32 s0, 0x60
	v_add_u32_e32 v11, 0x2000, v0
	v_or_b32_e32 v1, v8, v9
	v_and_or_b32 v3, v3, s0, v2
	v_lshrrev_b32_e32 v0, 7, v11
	s_movk_i32 s0, 0xf0
	s_add_u32 s30, s62, 0x4000000
	v_lshl_or_b32 v150, v4, 12, v1
	v_and_or_b32 v3, v0, s0, v10
	s_movk_i32 s0, 0xe0
	s_addc_u32 s31, s63, 0
	v_and_or_b32 v0, v0, s0, v2
	s_lshl_b32 s0, s2, 2
	s_and_b32 s0, s0, 28
	s_ashr_i32 s1, s2, 6
	s_add_i32 s0, s0, s1
	s_waitcnt lgkmcnt(0)
	s_bfe_u32 s16, s2, 0x30003
	s_ashr_i32 s1, s0, 31
	s_lshl_b64 s[6:7], s[0:1], 20
	s_lshl_b32 s2, s16, 20
	s_add_u32 s1, s62, s2
	s_addc_u32 s3, s63, 0
	s_add_u32 s4, s1, 0x1200000
	s_addc_u32 s5, s3, 0
	s_add_u32 s8, s1, 0x1280000
	s_addc_u32 s9, s3, 0
	s_add_u32 s6, s30, s6
	s_addc_u32 s7, s31, s7
	s_add_u32 s10, s6, 0x80000
	v_readfirstlane_b32 s3, v144
	s_addc_u32 s11, s7, 0
	s_lshr_b32 s18, s3, 6
	s_lshl_b32 s1, s18, 10
	s_add_i32 s34, s1, 0
	s_add_i32 m0, s34, 0x10000
	v_lshl_or_b32 v154, v3, 12, v1
	global_load_lds_dwordx4 v150, s[4:5]
	s_add_i32 m0, s34, 0x12000
	v_lshl_or_b32 v148, v4, 12, v1
	global_load_lds_dwordx4 v154, s[4:5]
	s_add_i32 m0, s34, 0x14000
	s_add_i32 s35, s34, 0x2000
	global_load_lds_dwordx4 v150, s[8:9]
	s_add_i32 m0, s34, 0x16000
	v_lshl_or_b32 v152, v3, 12, v1
	global_load_lds_dwordx4 v154, s[8:9]
	s_mov_b32 m0, s34
	s_add_i32 s36, s34, 0x4000
	global_load_lds_dwordx4 v148, s[6:7]
	s_mov_b32 m0, s35
	s_add_i32 s37, s34, 0x6000
	global_load_lds_dwordx4 v152, s[6:7]
	s_mov_b32 m0, s36
	v_mov_b32_e32 v151, 0
	global_load_lds_dwordx4 v148, s[10:11]
	s_mov_b32 m0, s37
	s_lshr_b32 s19, s3, 8
	global_load_lds_dwordx4 v152, s[10:11]
	v_mov_b32_e32 v155, v151
	v_mov_b32_e32 v149, v151
	v_mov_b32_e32 v153, v151
	s_cmp_eq_u32 s19, 1
	s_mov_b32 s38, 0
	v_lshl_add_u64 v[0:1], s[4:5], 0, v[150:151]
	v_lshl_add_u64 v[2:3], s[4:5], 0, v[154:155]
	v_lshl_add_u64 v[4:5], s[6:7], 0, v[148:149]
	s_cselect_b64 s[8:9], -1, 0
	s_cmp_lg_u32 s19, 1
	v_lshl_add_u64 v[6:7], s[6:7], 0, v[152:153]
	s_cbranch_scc1 .LBB0_525
	s_barrier
